# rotary-key projection item: k loop flattened, loads two half-trips ahead through a 3-deep register ring
# speedup vs baseline: 1.0057x; 1.0057x over previous
.LBB0_568:
	s_mov_b32 s6, 0x18e0000
	v_add_co_u32_e32 v160, vcc, s6, v18
	s_nop 1
	v_addc_co_u32_e32 v161, vcc, 0, v19, vcc
	s_mov_b32 s6, 0x18e8000
	v_add_co_u32_e32 v162, vcc, s6, v18
	s_nop 1
	v_addc_co_u32_e32 v163, vcc, 0, v19, vcc
	s_mov_b32 s6, 0xf9e0000
	v_add_co_u32_e32 v164, vcc, s6, v16
	s_nop 1
	v_addc_co_u32_e32 v165, vcc, 0, v17, vcc
	s_mov_b32 s6, 0xf9e8000
	v_add_co_u32_e32 v166, vcc, s6, v16
	s_nop 1
	v_addc_co_u32_e32 v167, vcc, 0, v17, vcc
	global_load_dwordx4 v[64:67], v[160:161], off
	global_load_dwordx4 v[68:71], v[162:163], off
	global_load_dwordx4 v[72:75], v[164:165], off
	global_load_dwordx4 v[76:79], v[166:167], off
	global_load_dwordx4 v[80:83], v[160:161], off offset:64
	global_load_dwordx4 v[84:87], v[162:163], off offset:64
	global_load_dwordx4 v[88:91], v[164:165], off offset:64
	global_load_dwordx4 v[92:95], v[166:167], off offset:64
	global_load_dwordx4 v[96:99], v[160:161], off offset:128
	global_load_dwordx4 v[100:103], v[162:163], off offset:128
	global_load_dwordx4 v[104:107], v[164:165], off offset:128
	global_load_dwordx4 v[108:111], v[166:167], off offset:128
	global_load_dwordx4 v[112:115], v[160:161], off offset:192
	global_load_dwordx4 v[116:119], v[162:163], off offset:192
	global_load_dwordx4 v[120:123], v[164:165], off offset:192
	global_load_dwordx4 v[124:127], v[166:167], off offset:192
	global_load_dwordx4 v[128:131], v[160:161], off offset:256
	global_load_dwordx4 v[132:135], v[162:163], off offset:256
	global_load_dwordx4 v[136:139], v[164:165], off offset:256
	global_load_dwordx4 v[140:143], v[166:167], off offset:256
	global_load_dwordx4 v[144:147], v[160:161], off offset:320
	global_load_dwordx4 v[148:151], v[162:163], off offset:320
	global_load_dwordx4 v[152:155], v[164:165], off offset:320
	global_load_dwordx4 v[156:159], v[166:167], off offset:320
	s_waitcnt vmcnt(20)
	v_mfma_f32_16x16x32_bf16 v[8:11], v[72:75], v[64:67], v[8:11]
	v_mfma_f32_16x16x32_bf16 v[12:15], v[76:79], v[64:67], v[12:15]
	v_mfma_f32_16x16x32_bf16 v[0:3], v[72:75], v[68:71], v[0:3]
	v_mfma_f32_16x16x32_bf16 v[4:7], v[76:79], v[68:71], v[4:7]
	s_waitcnt vmcnt(16)
	v_mfma_f32_16x16x32_bf16 v[8:11], v[88:91], v[80:83], v[8:11]
	v_mfma_f32_16x16x32_bf16 v[12:15], v[92:95], v[80:83], v[12:15]
	v_mfma_f32_16x16x32_bf16 v[0:3], v[88:91], v[84:87], v[0:3]
	v_mfma_f32_16x16x32_bf16 v[4:7], v[92:95], v[84:87], v[4:7]
	global_load_dwordx4 v[64:67], v[160:161], off offset:384
	global_load_dwordx4 v[68:71], v[162:163], off offset:384
	global_load_dwordx4 v[72:75], v[164:165], off offset:384
	global_load_dwordx4 v[76:79], v[166:167], off offset:384
	global_load_dwordx4 v[80:83], v[160:161], off offset:448
	global_load_dwordx4 v[84:87], v[162:163], off offset:448
	global_load_dwordx4 v[88:91], v[164:165], off offset:448
	global_load_dwordx4 v[92:95], v[166:167], off offset:448
	s_waitcnt vmcnt(20)
	v_mfma_f32_16x16x32_bf16 v[8:11], v[104:107], v[96:99], v[8:11]
	v_mfma_f32_16x16x32_bf16 v[12:15], v[108:111], v[96:99], v[12:15]
	v_mfma_f32_16x16x32_bf16 v[0:3], v[104:107], v[100:103], v[0:3]
	v_mfma_f32_16x16x32_bf16 v[4:7], v[108:111], v[100:103], v[4:7]
	s_waitcnt vmcnt(16)
	v_mfma_f32_16x16x32_bf16 v[8:11], v[120:123], v[112:115], v[8:11]
	v_mfma_f32_16x16x32_bf16 v[12:15], v[124:127], v[112:115], v[12:15]
	v_mfma_f32_16x16x32_bf16 v[0:3], v[120:123], v[116:119], v[0:3]
	v_mfma_f32_16x16x32_bf16 v[4:7], v[124:127], v[116:119], v[4:7]
	global_load_dwordx4 v[96:99], v[160:161], off offset:512
	global_load_dwordx4 v[100:103], v[162:163], off offset:512
	global_load_dwordx4 v[104:107], v[164:165], off offset:512
	global_load_dwordx4 v[108:111], v[166:167], off offset:512
	global_load_dwordx4 v[112:115], v[160:161], off offset:576
	global_load_dwordx4 v[116:119], v[162:163], off offset:576
	global_load_dwordx4 v[120:123], v[164:165], off offset:576
	global_load_dwordx4 v[124:127], v[166:167], off offset:576
	s_waitcnt vmcnt(20)
	v_mfma_f32_16x16x32_bf16 v[8:11], v[136:139], v[128:131], v[8:11]
	v_mfma_f32_16x16x32_bf16 v[12:15], v[140:143], v[128:131], v[12:15]
	v_mfma_f32_16x16x32_bf16 v[0:3], v[136:139], v[132:135], v[0:3]
	v_mfma_f32_16x16x32_bf16 v[4:7], v[140:143], v[132:135], v[4:7]
	s_waitcnt vmcnt(16)
	v_mfma_f32_16x16x32_bf16 v[8:11], v[152:155], v[144:147], v[8:11]
	v_mfma_f32_16x16x32_bf16 v[12:15], v[156:159], v[144:147], v[12:15]
	v_mfma_f32_16x16x32_bf16 v[0:3], v[152:155], v[148:151], v[0:3]
	v_mfma_f32_16x16x32_bf16 v[4:7], v[156:159], v[148:151], v[4:7]
	global_load_dwordx4 v[128:131], v[160:161], off offset:640
	global_load_dwordx4 v[132:135], v[162:163], off offset:640
	global_load_dwordx4 v[136:139], v[164:165], off offset:640
	global_load_dwordx4 v[140:143], v[166:167], off offset:640
	global_load_dwordx4 v[144:147], v[160:161], off offset:704
	global_load_dwordx4 v[148:151], v[162:163], off offset:704
	global_load_dwordx4 v[152:155], v[164:165], off offset:704
	global_load_dwordx4 v[156:159], v[166:167], off offset:704
	s_waitcnt vmcnt(20)
	v_mfma_f32_16x16x32_bf16 v[8:11], v[72:75], v[64:67], v[8:11]
	v_mfma_f32_16x16x32_bf16 v[12:15], v[76:79], v[64:67], v[12:15]
	v_mfma_f32_16x16x32_bf16 v[0:3], v[72:75], v[68:71], v[0:3]
	v_mfma_f32_16x16x32_bf16 v[4:7], v[76:79], v[68:71], v[4:7]
	s_waitcnt vmcnt(16)
	v_mfma_f32_16x16x32_bf16 v[8:11], v[88:91], v[80:83], v[8:11]
	v_mfma_f32_16x16x32_bf16 v[12:15], v[92:95], v[80:83], v[12:15]
	v_mfma_f32_16x16x32_bf16 v[0:3], v[88:91], v[84:87], v[0:3]
	v_mfma_f32_16x16x32_bf16 v[4:7], v[92:95], v[84:87], v[4:7]
	global_load_dwordx4 v[64:67], v[160:161], off offset:768
	global_load_dwordx4 v[68:71], v[162:163], off offset:768
	global_load_dwordx4 v[72:75], v[164:165], off offset:768
	global_load_dwordx4 v[76:79], v[166:167], off offset:768
	global_load_dwordx4 v[80:83], v[160:161], off offset:832
	global_load_dwordx4 v[84:87], v[162:163], off offset:832
	global_load_dwordx4 v[88:91], v[164:165], off offset:832
	global_load_dwordx4 v[92:95], v[166:167], off offset:832
	s_waitcnt vmcnt(20)
	v_mfma_f32_16x16x32_bf16 v[8:11], v[104:107], v[96:99], v[8:11]
	v_mfma_f32_16x16x32_bf16 v[12:15], v[108:111], v[96:99], v[12:15]
	v_mfma_f32_16x16x32_bf16 v[0:3], v[104:107], v[100:103], v[0:3]
	v_mfma_f32_16x16x32_bf16 v[4:7], v[108:111], v[100:103], v[4:7]
	s_waitcnt vmcnt(16)
	v_mfma_f32_16x16x32_bf16 v[8:11], v[120:123], v[112:115], v[8:11]
	v_mfma_f32_16x16x32_bf16 v[12:15], v[124:127], v[112:115], v[12:15]
	v_mfma_f32_16x16x32_bf16 v[0:3], v[120:123], v[116:119], v[0:3]
	v_mfma_f32_16x16x32_bf16 v[4:7], v[124:127], v[116:119], v[4:7]
	global_load_dwordx4 v[96:99], v[160:161], off offset:896
	global_load_dwordx4 v[100:103], v[162:163], off offset:896
	global_load_dwordx4 v[104:107], v[164:165], off offset:896
	global_load_dwordx4 v[108:111], v[166:167], off offset:896
	global_load_dwordx4 v[112:115], v[160:161], off offset:960
	global_load_dwordx4 v[116:119], v[162:163], off offset:960
	global_load_dwordx4 v[120:123], v[164:165], off offset:960
	global_load_dwordx4 v[124:127], v[166:167], off offset:960
	s_waitcnt vmcnt(20)
	v_mfma_f32_16x16x32_bf16 v[8:11], v[136:139], v[128:131], v[8:11]
	v_mfma_f32_16x16x32_bf16 v[12:15], v[140:143], v[128:131], v[12:15]
	v_mfma_f32_16x16x32_bf16 v[0:3], v[136:139], v[132:135], v[0:3]
	v_mfma_f32_16x16x32_bf16 v[4:7], v[140:143], v[132:135], v[4:7]
	s_waitcnt vmcnt(16)
	v_mfma_f32_16x16x32_bf16 v[8:11], v[152:155], v[144:147], v[8:11]
	v_mfma_f32_16x16x32_bf16 v[12:15], v[156:159], v[144:147], v[12:15]
	v_mfma_f32_16x16x32_bf16 v[0:3], v[152:155], v[148:151], v[0:3]
	v_mfma_f32_16x16x32_bf16 v[4:7], v[156:159], v[148:151], v[4:7]
	global_load_dwordx4 v[128:131], v[160:161], off offset:1024
	global_load_dwordx4 v[132:135], v[162:163], off offset:1024
	global_load_dwordx4 v[136:139], v[164:165], off offset:1024
	global_load_dwordx4 v[140:143], v[166:167], off offset:1024
	global_load_dwordx4 v[144:147], v[160:161], off offset:1088
	global_load_dwordx4 v[148:151], v[162:163], off offset:1088
	global_load_dwordx4 v[152:155], v[164:165], off offset:1088
	global_load_dwordx4 v[156:159], v[166:167], off offset:1088
	s_waitcnt vmcnt(20)
	v_mfma_f32_16x16x32_bf16 v[8:11], v[72:75], v[64:67], v[8:11]
	v_mfma_f32_16x16x32_bf16 v[12:15], v[76:79], v[64:67], v[12:15]
	v_mfma_f32_16x16x32_bf16 v[0:3], v[72:75], v[68:71], v[0:3]
	v_mfma_f32_16x16x32_bf16 v[4:7], v[76:79], v[68:71], v[4:7]
	s_waitcnt vmcnt(16)
	v_mfma_f32_16x16x32_bf16 v[8:11], v[88:91], v[80:83], v[8:11]
	v_mfma_f32_16x16x32_bf16 v[12:15], v[92:95], v[80:83], v[12:15]
	v_mfma_f32_16x16x32_bf16 v[0:3], v[88:91], v[84:87], v[0:3]
	v_mfma_f32_16x16x32_bf16 v[4:7], v[92:95], v[84:87], v[4:7]
	global_load_dwordx4 v[64:67], v[160:161], off offset:1152
	global_load_dwordx4 v[68:71], v[162:163], off offset:1152
	global_load_dwordx4 v[72:75], v[164:165], off offset:1152
	global_load_dwordx4 v[76:79], v[166:167], off offset:1152
	global_load_dwordx4 v[80:83], v[160:161], off offset:1216
	global_load_dwordx4 v[84:87], v[162:163], off offset:1216
	global_load_dwordx4 v[88:91], v[164:165], off offset:1216
	global_load_dwordx4 v[92:95], v[166:167], off offset:1216
	s_waitcnt vmcnt(20)
	v_mfma_f32_16x16x32_bf16 v[8:11], v[104:107], v[96:99], v[8:11]
	v_mfma_f32_16x16x32_bf16 v[12:15], v[108:111], v[96:99], v[12:15]
	v_mfma_f32_16x16x32_bf16 v[0:3], v[104:107], v[100:103], v[0:3]
	v_mfma_f32_16x16x32_bf16 v[4:7], v[108:111], v[100:103], v[4:7]
	s_waitcnt vmcnt(16)
	v_mfma_f32_16x16x32_bf16 v[8:11], v[120:123], v[112:115], v[8:11]
	v_mfma_f32_16x16x32_bf16 v[12:15], v[124:127], v[112:115], v[12:15]
	v_mfma_f32_16x16x32_bf16 v[0:3], v[120:123], v[116:119], v[0:3]
	v_mfma_f32_16x16x32_bf16 v[4:7], v[124:127], v[116:119], v[4:7]
	global_load_dwordx4 v[96:99], v[160:161], off offset:1280
	global_load_dwordx4 v[100:103], v[162:163], off offset:1280
	global_load_dwordx4 v[104:107], v[164:165], off offset:1280
	global_load_dwordx4 v[108:111], v[166:167], off offset:1280
	global_load_dwordx4 v[112:115], v[160:161], off offset:1344
	global_load_dwordx4 v[116:119], v[162:163], off offset:1344
	global_load_dwordx4 v[120:123], v[164:165], off offset:1344
	global_load_dwordx4 v[124:127], v[166:167], off offset:1344
	s_waitcnt vmcnt(20)
	v_mfma_f32_16x16x32_bf16 v[8:11], v[136:139], v[128:131], v[8:11]
	v_mfma_f32_16x16x32_bf16 v[12:15], v[140:143], v[128:131], v[12:15]
	v_mfma_f32_16x16x32_bf16 v[0:3], v[136:139], v[132:135], v[0:3]
	v_mfma_f32_16x16x32_bf16 v[4:7], v[140:143], v[132:135], v[4:7]
	s_waitcnt vmcnt(16)
	v_mfma_f32_16x16x32_bf16 v[8:11], v[152:155], v[144:147], v[8:11]
	v_mfma_f32_16x16x32_bf16 v[12:15], v[156:159], v[144:147], v[12:15]
	v_mfma_f32_16x16x32_bf16 v[0:3], v[152:155], v[148:151], v[0:3]
	v_mfma_f32_16x16x32_bf16 v[4:7], v[156:159], v[148:151], v[4:7]
	global_load_dwordx4 v[128:131], v[160:161], off offset:1408
	global_load_dwordx4 v[132:135], v[162:163], off offset:1408
	global_load_dwordx4 v[136:139], v[164:165], off offset:1408
	global_load_dwordx4 v[140:143], v[166:167], off offset:1408
	global_load_dwordx4 v[144:147], v[160:161], off offset:1472
	global_load_dwordx4 v[148:151], v[162:163], off offset:1472
	global_load_dwordx4 v[152:155], v[164:165], off offset:1472
	global_load_dwordx4 v[156:159], v[166:167], off offset:1472
	s_waitcnt vmcnt(20)
	v_mfma_f32_16x16x32_bf16 v[8:11], v[72:75], v[64:67], v[8:11]
	v_mfma_f32_16x16x32_bf16 v[12:15], v[76:79], v[64:67], v[12:15]
	v_mfma_f32_16x16x32_bf16 v[0:3], v[72:75], v[68:71], v[0:3]
	v_mfma_f32_16x16x32_bf16 v[4:7], v[76:79], v[68:71], v[4:7]
	s_waitcnt vmcnt(16)
	v_mfma_f32_16x16x32_bf16 v[8:11], v[88:91], v[80:83], v[8:11]
	v_mfma_f32_16x16x32_bf16 v[12:15], v[92:95], v[80:83], v[12:15]
	v_mfma_f32_16x16x32_bf16 v[0:3], v[88:91], v[84:87], v[0:3]
	v_mfma_f32_16x16x32_bf16 v[4:7], v[92:95], v[84:87], v[4:7]
	global_load_dwordx4 v[64:67], v[160:161], off offset:1536
	global_load_dwordx4 v[68:71], v[162:163], off offset:1536
	global_load_dwordx4 v[72:75], v[164:165], off offset:1536
	global_load_dwordx4 v[76:79], v[166:167], off offset:1536
	global_load_dwordx4 v[80:83], v[160:161], off offset:1600
	global_load_dwordx4 v[84:87], v[162:163], off offset:1600
	global_load_dwordx4 v[88:91], v[164:165], off offset:1600
	global_load_dwordx4 v[92:95], v[166:167], off offset:1600
	s_waitcnt vmcnt(20)
	v_mfma_f32_16x16x32_bf16 v[8:11], v[104:107], v[96:99], v[8:11]
	v_mfma_f32_16x16x32_bf16 v[12:15], v[108:111], v[96:99], v[12:15]
	v_mfma_f32_16x16x32_bf16 v[0:3], v[104:107], v[100:103], v[0:3]
	v_mfma_f32_16x16x32_bf16 v[4:7], v[108:111], v[100:103], v[4:7]
	s_waitcnt vmcnt(16)
	v_mfma_f32_16x16x32_bf16 v[8:11], v[120:123], v[112:115], v[8:11]
	v_mfma_f32_16x16x32_bf16 v[12:15], v[124:127], v[112:115], v[12:15]
	v_mfma_f32_16x16x32_bf16 v[0:3], v[120:123], v[116:119], v[0:3]
	v_mfma_f32_16x16x32_bf16 v[4:7], v[124:127], v[116:119], v[4:7]
	global_load_dwordx4 v[96:99], v[160:161], off offset:1664
	global_load_dwordx4 v[100:103], v[162:163], off offset:1664
	global_load_dwordx4 v[104:107], v[164:165], off offset:1664
	global_load_dwordx4 v[108:111], v[166:167], off offset:1664
	global_load_dwordx4 v[112:115], v[160:161], off offset:1728
	global_load_dwordx4 v[116:119], v[162:163], off offset:1728
	global_load_dwordx4 v[120:123], v[164:165], off offset:1728
	global_load_dwordx4 v[124:127], v[166:167], off offset:1728
	s_waitcnt vmcnt(20)
	v_mfma_f32_16x16x32_bf16 v[8:11], v[136:139], v[128:131], v[8:11]
	v_mfma_f32_16x16x32_bf16 v[12:15], v[140:143], v[128:131], v[12:15]
	v_mfma_f32_16x16x32_bf16 v[0:3], v[136:139], v[132:135], v[0:3]
	v_mfma_f32_16x16x32_bf16 v[4:7], v[140:143], v[132:135], v[4:7]
	s_waitcnt vmcnt(16)
	v_mfma_f32_16x16x32_bf16 v[8:11], v[152:155], v[144:147], v[8:11]
	v_mfma_f32_16x16x32_bf16 v[12:15], v[156:159], v[144:147], v[12:15]
	v_mfma_f32_16x16x32_bf16 v[0:3], v[152:155], v[148:151], v[0:3]
	v_mfma_f32_16x16x32_bf16 v[4:7], v[156:159], v[148:151], v[4:7]
	global_load_dwordx4 v[128:131], v[160:161], off offset:1792
	global_load_dwordx4 v[132:135], v[162:163], off offset:1792
	global_load_dwordx4 v[136:139], v[164:165], off offset:1792
	global_load_dwordx4 v[140:143], v[166:167], off offset:1792
	global_load_dwordx4 v[144:147], v[160:161], off offset:1856
	global_load_dwordx4 v[148:151], v[162:163], off offset:1856
	global_load_dwordx4 v[152:155], v[164:165], off offset:1856
	global_load_dwordx4 v[156:159], v[166:167], off offset:1856
	s_waitcnt vmcnt(20)
	v_mfma_f32_16x16x32_bf16 v[8:11], v[72:75], v[64:67], v[8:11]
	v_mfma_f32_16x16x32_bf16 v[12:15], v[76:79], v[64:67], v[12:15]
	v_mfma_f32_16x16x32_bf16 v[0:3], v[72:75], v[68:71], v[0:3]
	v_mfma_f32_16x16x32_bf16 v[4:7], v[76:79], v[68:71], v[4:7]
	s_waitcnt vmcnt(16)
	v_mfma_f32_16x16x32_bf16 v[8:11], v[88:91], v[80:83], v[8:11]
	v_mfma_f32_16x16x32_bf16 v[12:15], v[92:95], v[80:83], v[12:15]
	v_mfma_f32_16x16x32_bf16 v[0:3], v[88:91], v[84:87], v[0:3]
	v_mfma_f32_16x16x32_bf16 v[4:7], v[92:95], v[84:87], v[4:7]
	global_load_dwordx4 v[64:67], v[160:161], off offset:1920
	global_load_dwordx4 v[68:71], v[162:163], off offset:1920
	global_load_dwordx4 v[72:75], v[164:165], off offset:1920
	global_load_dwordx4 v[76:79], v[166:167], off offset:1920
	global_load_dwordx4 v[80:83], v[160:161], off offset:1984
	global_load_dwordx4 v[84:87], v[162:163], off offset:1984
	global_load_dwordx4 v[88:91], v[164:165], off offset:1984
	global_load_dwordx4 v[92:95], v[166:167], off offset:1984
	s_waitcnt vmcnt(20)
	v_mfma_f32_16x16x32_bf16 v[8:11], v[104:107], v[96:99], v[8:11]
	v_mfma_f32_16x16x32_bf16 v[12:15], v[108:111], v[96:99], v[12:15]
	v_mfma_f32_16x16x32_bf16 v[0:3], v[104:107], v[100:103], v[0:3]
	v_mfma_f32_16x16x32_bf16 v[4:7], v[108:111], v[100:103], v[4:7]
	s_waitcnt vmcnt(16)
	v_mfma_f32_16x16x32_bf16 v[8:11], v[120:123], v[112:115], v[8:11]
	v_mfma_f32_16x16x32_bf16 v[12:15], v[124:127], v[112:115], v[12:15]
	v_mfma_f32_16x16x32_bf16 v[0:3], v[120:123], v[116:119], v[0:3]
	v_mfma_f32_16x16x32_bf16 v[4:7], v[124:127], v[116:119], v[4:7]
	s_waitcnt vmcnt(12)
	v_mfma_f32_16x16x32_bf16 v[8:11], v[136:139], v[128:131], v[8:11]
	v_mfma_f32_16x16x32_bf16 v[12:15], v[140:143], v[128:131], v[12:15]
	v_mfma_f32_16x16x32_bf16 v[0:3], v[136:139], v[132:135], v[0:3]
	v_mfma_f32_16x16x32_bf16 v[4:7], v[140:143], v[132:135], v[4:7]
	s_waitcnt vmcnt(8)
	v_mfma_f32_16x16x32_bf16 v[8:11], v[152:155], v[144:147], v[8:11]
	v_mfma_f32_16x16x32_bf16 v[12:15], v[156:159], v[144:147], v[12:15]
	v_mfma_f32_16x16x32_bf16 v[0:3], v[152:155], v[148:151], v[0:3]
	v_mfma_f32_16x16x32_bf16 v[4:7], v[156:159], v[148:151], v[4:7]
	s_waitcnt vmcnt(4)
	v_mfma_f32_16x16x32_bf16 v[8:11], v[72:75], v[64:67], v[8:11]
	v_mfma_f32_16x16x32_bf16 v[12:15], v[76:79], v[64:67], v[12:15]
	v_mfma_f32_16x16x32_bf16 v[0:3], v[72:75], v[68:71], v[0:3]
	v_mfma_f32_16x16x32_bf16 v[4:7], v[76:79], v[68:71], v[4:7]
	s_waitcnt vmcnt(0)
	v_mfma_f32_16x16x32_bf16 v[8:11], v[88:91], v[80:83], v[8:11]
	v_mfma_f32_16x16x32_bf16 v[12:15], v[92:95], v[80:83], v[12:15]
	v_mfma_f32_16x16x32_bf16 v[0:3], v[88:91], v[84:87], v[0:3]
	v_mfma_f32_16x16x32_bf16 v[4:7], v[92:95], v[84:87], v[4:7]
	s_movk_i32 s4, 0x800
	s_mov_b32 s5, 0
	v_or_b32_e32 v16, v22, v20
	v_add_u32_e32 v16, v16, v21
	v_ashrrev_i32_e32 v17, 31, v16
	s_waitcnt lgkmcnt(0)
	v_lshl_add_u64 v[18:19], v[16:17], 2, s[24:25]
	global_load_dword v17, v[18:19], off
	v_and_b32_e32 v28, 3, v23
	v_lshlrev_b32_e32 v27, 2, v28
	v_lshlrev_b32_e32 v168, 3, v28
	s_waitcnt vmcnt(0)
	v_cvt_f32_i32_e32 v29, v17
	v_cvt_f32_ubyte0_e32 v17, v27
	v_mul_f32_e32 v18, 0xbf549a78, v17
	v_cmp_gt_f32_e32 vcc, s91, v18
	s_nop 1
	v_cndmask_b32_e32 v18, 0, v180, vcc
	v_fmac_f32_e32 v18, 0xbf549a78, v17
	v_exp_f32_e32 v17, v18
	v_cndmask_b32_e32 v18, 0, v179, vcc
	v_ldexp_f32 v17, v17, v18
	v_mul_f32_e32 v18, v17, v29
	v_mul_f32_e32 v19, 0.15915494, v18
	v_rndne_f32_e32 v19, v19
	v_fma_f32 v19, v18, 0.15915494, -v19
	v_fmac_f32_e32 v19, 0x31dc9c88, v18
	v_or_b32_e32 v18, 1, v27
	v_cvt_f32_ubyte0_e32 v18, v18
	v_sin_f32_e32 v20, v19
	v_cos_f32_e32 v24, v19
	v_mul_f32_e32 v19, 0xbf549a78, v18
	v_cmp_gt_f32_e32 vcc, s91, v19
	s_nop 1
	v_cndmask_b32_e32 v19, 0, v180, vcc
	v_fmac_f32_e32 v19, 0xbf549a78, v18
	v_exp_f32_e32 v18, v19
	v_cndmask_b32_e32 v19, 0, v179, vcc
	v_ldexp_f32 v22, v18, v19
	v_mul_f32_e32 v18, v22, v29
	v_mul_f32_e32 v19, 0.15915494, v18
	v_rndne_f32_e32 v19, v19
	v_fma_f32 v19, v18, 0.15915494, -v19
	v_fmac_f32_e32 v19, 0x31dc9c88, v18
	v_sin_f32_e32 v21, v19
	v_cos_f32_e32 v25, v19
	v_pk_mul_f32 v[18:19], v[12:13], v[20:21]
	v_pk_mul_f32 v[12:13], v[12:13], v[24:25]
	v_pk_fma_f32 v[18:19], v[8:9], v[24:25], v[18:19] neg_lo:[0,0,1] neg_hi:[0,0,1]
	v_pk_fma_f32 v[12:13], v[8:9], v[20:21], v[12:13]
	v_or_b32_e32 v8, 2, v27
	v_cvt_f32_ubyte0_e32 v8, v8
	v_mul_f32_e32 v9, 0xbf549a78, v8
	v_cmp_gt_f32_e32 vcc, s91, v9
	v_cvt_pk_bf16_f32 v12, v12, v13
	v_cvt_pk_bf16_f32 v18, v18, v19
	v_cndmask_b32_e32 v9, 0, v180, vcc
	v_fmac_f32_e32 v9, 0xbf549a78, v8
	v_exp_f32_e32 v8, v9
	v_cndmask_b32_e32 v9, 0, v179, vcc
	v_ldexp_f32 v23, v8, v9
	v_mul_f32_e32 v8, v23, v29
	v_mul_f32_e32 v9, 0.15915494, v8
	v_rndne_f32_e32 v9, v9
	v_fma_f32 v9, v8, 0.15915494, -v9
	v_fmac_f32_e32 v9, 0x31dc9c88, v8
	v_sin_f32_e32 v8, v9
	v_cos_f32_e32 v26, v9
	v_or_b32_e32 v9, 3, v27
	v_cvt_f32_ubyte0_e32 v9, v9
	v_mul_f32_e32 v20, 0xbf549a78, v9
	v_cmp_gt_f32_e32 vcc, s91, v20
	s_nop 1
	v_cndmask_b32_e32 v20, 0, v180, vcc
	v_fmac_f32_e32 v20, 0xbf549a78, v9
	v_exp_f32_e32 v9, v20
	v_cndmask_b32_e32 v20, 0, v179, vcc
	v_ldexp_f32 v24, v9, v20
	v_mul_f32_e32 v9, v24, v29
	v_mul_f32_e32 v20, 0.15915494, v9
	v_rndne_f32_e32 v20, v20
	v_fma_f32 v20, v9, 0.15915494, -v20
	v_fmac_f32_e32 v20, 0x31dc9c88, v9
	v_sin_f32_e32 v9, v20
	v_cos_f32_e32 v27, v20
	v_pk_mul_f32 v[20:21], v[14:15], v[8:9]
	v_pk_mul_f32 v[14:15], v[14:15], v[26:27]
	v_pk_fma_f32 v[20:21], v[10:11], v[26:27], v[20:21] neg_lo:[0,0,1] neg_hi:[0,0,1]
	v_pk_fma_f32 v[10:11], v[10:11], v[8:9], v[14:15]
	v_mov_b64_e32 v[8:9], s[62:63]
	v_mad_i64_i32 v[14:15], s[4:5], v16, s59, v[8:9]
	v_lshl_add_u64 v[14:15], v[14:15], 0, v[168:169]
	s_mov_b32 s4, 0x38e2000
	v_lshl_add_u64 v[26:27], v[14:15], 0, s[80:81]
	v_add_co_u32_e32 v14, vcc, s4, v14
	v_cvt_pk_bf16_f32 v13, v10, v11
	v_or_b32_e32 v10, 16, v16
	v_cvt_pk_bf16_f32 v19, v20, v21
	v_addc_co_u32_e32 v15, vcc, 0, v15, vcc
	v_ashrrev_i32_e32 v11, 31, v10
	global_store_dwordx2 v[14:15], v[18:19], off offset:2048
	global_store_dwordx2 v[26:27], v[12:13], off offset:32
	v_lshl_add_u64 v[12:13], v[10:11], 2, s[24:25]
	global_load_dword v11, v[12:13], off
	s_waitcnt vmcnt(0)
	v_cvt_f32_i32_e32 v11, v11
	v_mul_f32_e32 v12, v17, v11
	v_mul_f32_e32 v13, 0.15915494, v12
	v_rndne_f32_e32 v13, v13
	v_fma_f32 v13, v12, 0.15915494, -v13
	v_fmac_f32_e32 v13, 0x31dc9c88, v12
	v_sin_f32_e32 v12, v13
	v_cos_f32_e32 v14, v13
	v_mul_f32_e32 v13, v22, v11
	v_mul_f32_e32 v15, 0.15915494, v13
	v_rndne_f32_e32 v15, v15
	v_fma_f32 v15, v13, 0.15915494, -v15
	v_fmac_f32_e32 v15, 0x31dc9c88, v13
	v_sin_f32_e32 v13, v15
	v_cos_f32_e32 v15, v15
	v_pk_mul_f32 v[16:17], v[4:5], v[12:13]
	v_pk_mul_f32 v[4:5], v[4:5], v[14:15]
	v_pk_fma_f32 v[16:17], v[0:1], v[14:15], v[16:17] neg_lo:[0,0,1] neg_hi:[0,0,1]
	v_pk_fma_f32 v[0:1], v[0:1], v[12:13], v[4:5]
	v_mul_f32_e32 v4, v23, v11
	v_mul_f32_e32 v5, 0.15915494, v4
	v_rndne_f32_e32 v5, v5
	v_fma_f32 v5, v4, 0.15915494, -v5
	v_fmac_f32_e32 v5, 0x31dc9c88, v4
	v_sin_f32_e32 v4, v5
	v_cos_f32_e32 v12, v5
	v_mul_f32_e32 v5, v24, v11
	v_mul_f32_e32 v11, 0.15915494, v5
	v_rndne_f32_e32 v11, v11
	v_fma_f32 v11, v5, 0.15915494, -v11
	v_fmac_f32_e32 v11, 0x31dc9c88, v5
	v_sin_f32_e32 v5, v11
	v_cos_f32_e32 v13, v11
	v_cvt_pk_bf16_f32 v0, v0, v1
	v_pk_mul_f32 v[14:15], v[6:7], v[4:5]
	v_pk_mul_f32 v[6:7], v[6:7], v[12:13]
	v_pk_fma_f32 v[14:15], v[2:3], v[12:13], v[14:15] neg_lo:[0,0,1] neg_hi:[0,0,1]
	v_pk_fma_f32 v[2:3], v[2:3], v[4:5], v[6:7]
	v_mad_i64_i32 v[4:5], s[4:5], v10, s59, v[8:9]
	v_lshl_add_u64 v[4:5], v[4:5], 0, v[168:169]
	v_lshl_add_u64 v[6:7], v[4:5], 0, s[80:81]
	v_add_co_u32_e32 v4, vcc, 0x38e2000, v4
	v_cvt_pk_bf16_f32 v8, v16, v17
	v_cvt_pk_bf16_f32 v9, v14, v15
	v_addc_co_u32_e32 v5, vcc, 0, v5, vcc
	v_cvt_pk_bf16_f32 v1, v2, v3
	global_store_dwordx2 v[4:5], v[8:9], off offset:2048
	global_store_dwordx2 v[6:7], v[0:1], off offset:32

.LBB0_1334:
	s_mov_b32 s6, 0x18e0000
	v_add_co_u32_e32 v160, vcc, s6, v18
	s_nop 1
	v_addc_co_u32_e32 v161, vcc, 0, v19, vcc
	s_mov_b32 s6, 0x18e8000
	v_add_co_u32_e32 v162, vcc, s6, v18
	s_nop 1
	v_addc_co_u32_e32 v163, vcc, 0, v19, vcc
	s_mov_b32 s6, 0xf9e0000
	v_add_co_u32_e32 v164, vcc, s6, v16
	s_nop 1
	v_addc_co_u32_e32 v165, vcc, 0, v17, vcc
	s_mov_b32 s6, 0xf9e8000
	v_add_co_u32_e32 v166, vcc, s6, v16
	s_nop 1
	v_addc_co_u32_e32 v167, vcc, 0, v17, vcc
	global_load_dwordx4 v[64:67], v[160:161], off
	global_load_dwordx4 v[68:71], v[162:163], off
	global_load_dwordx4 v[72:75], v[164:165], off
	global_load_dwordx4 v[76:79], v[166:167], off
	global_load_dwordx4 v[80:83], v[160:161], off offset:64
	global_load_dwordx4 v[84:87], v[162:163], off offset:64
	global_load_dwordx4 v[88:91], v[164:165], off offset:64
	global_load_dwordx4 v[92:95], v[166:167], off offset:64
	global_load_dwordx4 v[96:99], v[160:161], off offset:128
	global_load_dwordx4 v[100:103], v[162:163], off offset:128
	global_load_dwordx4 v[104:107], v[164:165], off offset:128
	global_load_dwordx4 v[108:111], v[166:167], off offset:128
	global_load_dwordx4 v[112:115], v[160:161], off offset:192
	global_load_dwordx4 v[116:119], v[162:163], off offset:192
	global_load_dwordx4 v[120:123], v[164:165], off offset:192
	global_load_dwordx4 v[124:127], v[166:167], off offset:192
	global_load_dwordx4 v[128:131], v[160:161], off offset:256
	global_load_dwordx4 v[132:135], v[162:163], off offset:256
	global_load_dwordx4 v[136:139], v[164:165], off offset:256
	global_load_dwordx4 v[140:143], v[166:167], off offset:256
	global_load_dwordx4 v[144:147], v[160:161], off offset:320
	global_load_dwordx4 v[148:151], v[162:163], off offset:320
	global_load_dwordx4 v[152:155], v[164:165], off offset:320
	global_load_dwordx4 v[156:159], v[166:167], off offset:320
	s_waitcnt vmcnt(20)
	v_mfma_f32_16x16x32_bf16 v[8:11], v[72:75], v[64:67], v[8:11]
	v_mfma_f32_16x16x32_bf16 v[12:15], v[76:79], v[64:67], v[12:15]
	v_mfma_f32_16x16x32_bf16 v[0:3], v[72:75], v[68:71], v[0:3]
	v_mfma_f32_16x16x32_bf16 v[4:7], v[76:79], v[68:71], v[4:7]
	s_waitcnt vmcnt(16)
	v_mfma_f32_16x16x32_bf16 v[8:11], v[88:91], v[80:83], v[8:11]
	v_mfma_f32_16x16x32_bf16 v[12:15], v[92:95], v[80:83], v[12:15]
	v_mfma_f32_16x16x32_bf16 v[0:3], v[88:91], v[84:87], v[0:3]
	v_mfma_f32_16x16x32_bf16 v[4:7], v[92:95], v[84:87], v[4:7]
	global_load_dwordx4 v[64:67], v[160:161], off offset:384
	global_load_dwordx4 v[68:71], v[162:163], off offset:384
	global_load_dwordx4 v[72:75], v[164:165], off offset:384
	global_load_dwordx4 v[76:79], v[166:167], off offset:384
	global_load_dwordx4 v[80:83], v[160:161], off offset:448
	global_load_dwordx4 v[84:87], v[162:163], off offset:448
	global_load_dwordx4 v[88:91], v[164:165], off offset:448
	global_load_dwordx4 v[92:95], v[166:167], off offset:448
	s_waitcnt vmcnt(20)
	v_mfma_f32_16x16x32_bf16 v[8:11], v[104:107], v[96:99], v[8:11]
	v_mfma_f32_16x16x32_bf16 v[12:15], v[108:111], v[96:99], v[12:15]
	v_mfma_f32_16x16x32_bf16 v[0:3], v[104:107], v[100:103], v[0:3]
	v_mfma_f32_16x16x32_bf16 v[4:7], v[108:111], v[100:103], v[4:7]
	s_waitcnt vmcnt(16)
	v_mfma_f32_16x16x32_bf16 v[8:11], v[120:123], v[112:115], v[8:11]
	v_mfma_f32_16x16x32_bf16 v[12:15], v[124:127], v[112:115], v[12:15]
	v_mfma_f32_16x16x32_bf16 v[0:3], v[120:123], v[116:119], v[0:3]
	v_mfma_f32_16x16x32_bf16 v[4:7], v[124:127], v[116:119], v[4:7]
	global_load_dwordx4 v[96:99], v[160:161], off offset:512
	global_load_dwordx4 v[100:103], v[162:163], off offset:512
	global_load_dwordx4 v[104:107], v[164:165], off offset:512
	global_load_dwordx4 v[108:111], v[166:167], off offset:512
	global_load_dwordx4 v[112:115], v[160:161], off offset:576
	global_load_dwordx4 v[116:119], v[162:163], off offset:576
	global_load_dwordx4 v[120:123], v[164:165], off offset:576
	global_load_dwordx4 v[124:127], v[166:167], off offset:576
	s_waitcnt vmcnt(20)
	v_mfma_f32_16x16x32_bf16 v[8:11], v[136:139], v[128:131], v[8:11]
	v_mfma_f32_16x16x32_bf16 v[12:15], v[140:143], v[128:131], v[12:15]
	v_mfma_f32_16x16x32_bf16 v[0:3], v[136:139], v[132:135], v[0:3]
	v_mfma_f32_16x16x32_bf16 v[4:7], v[140:143], v[132:135], v[4:7]
	s_waitcnt vmcnt(16)
	v_mfma_f32_16x16x32_bf16 v[8:11], v[152:155], v[144:147], v[8:11]
	v_mfma_f32_16x16x32_bf16 v[12:15], v[156:159], v[144:147], v[12:15]
	v_mfma_f32_16x16x32_bf16 v[0:3], v[152:155], v[148:151], v[0:3]
	v_mfma_f32_16x16x32_bf16 v[4:7], v[156:159], v[148:151], v[4:7]
	global_load_dwordx4 v[128:131], v[160:161], off offset:640
	global_load_dwordx4 v[132:135], v[162:163], off offset:640
	global_load_dwordx4 v[136:139], v[164:165], off offset:640
	global_load_dwordx4 v[140:143], v[166:167], off offset:640
	global_load_dwordx4 v[144:147], v[160:161], off offset:704
	global_load_dwordx4 v[148:151], v[162:163], off offset:704
	global_load_dwordx4 v[152:155], v[164:165], off offset:704
	global_load_dwordx4 v[156:159], v[166:167], off offset:704
	s_waitcnt vmcnt(20)
	v_mfma_f32_16x16x32_bf16 v[8:11], v[72:75], v[64:67], v[8:11]
	v_mfma_f32_16x16x32_bf16 v[12:15], v[76:79], v[64:67], v[12:15]
	v_mfma_f32_16x16x32_bf16 v[0:3], v[72:75], v[68:71], v[0:3]
	v_mfma_f32_16x16x32_bf16 v[4:7], v[76:79], v[68:71], v[4:7]
	s_waitcnt vmcnt(16)
	v_mfma_f32_16x16x32_bf16 v[8:11], v[88:91], v[80:83], v[8:11]
	v_mfma_f32_16x16x32_bf16 v[12:15], v[92:95], v[80:83], v[12:15]
	v_mfma_f32_16x16x32_bf16 v[0:3], v[88:91], v[84:87], v[0:3]
	v_mfma_f32_16x16x32_bf16 v[4:7], v[92:95], v[84:87], v[4:7]
	global_load_dwordx4 v[64:67], v[160:161], off offset:768
	global_load_dwordx4 v[68:71], v[162:163], off offset:768
	global_load_dwordx4 v[72:75], v[164:165], off offset:768
	global_load_dwordx4 v[76:79], v[166:167], off offset:768
	global_load_dwordx4 v[80:83], v[160:161], off offset:832
	global_load_dwordx4 v[84:87], v[162:163], off offset:832
	global_load_dwordx4 v[88:91], v[164:165], off offset:832
	global_load_dwordx4 v[92:95], v[166:167], off offset:832
	s_waitcnt vmcnt(20)
	v_mfma_f32_16x16x32_bf16 v[8:11], v[104:107], v[96:99], v[8:11]
	v_mfma_f32_16x16x32_bf16 v[12:15], v[108:111], v[96:99], v[12:15]
	v_mfma_f32_16x16x32_bf16 v[0:3], v[104:107], v[100:103], v[0:3]
	v_mfma_f32_16x16x32_bf16 v[4:7], v[108:111], v[100:103], v[4:7]
	s_waitcnt vmcnt(16)
	v_mfma_f32_16x16x32_bf16 v[8:11], v[120:123], v[112:115], v[8:11]
	v_mfma_f32_16x16x32_bf16 v[12:15], v[124:127], v[112:115], v[12:15]
	v_mfma_f32_16x16x32_bf16 v[0:3], v[120:123], v[116:119], v[0:3]
	v_mfma_f32_16x16x32_bf16 v[4:7], v[124:127], v[116:119], v[4:7]
	global_load_dwordx4 v[96:99], v[160:161], off offset:896
	global_load_dwordx4 v[100:103], v[162:163], off offset:896
	global_load_dwordx4 v[104:107], v[164:165], off offset:896
	global_load_dwordx4 v[108:111], v[166:167], off offset:896
	global_load_dwordx4 v[112:115], v[160:161], off offset:960
	global_load_dwordx4 v[116:119], v[162:163], off offset:960
	global_load_dwordx4 v[120:123], v[164:165], off offset:960
	global_load_dwordx4 v[124:127], v[166:167], off offset:960
	s_waitcnt vmcnt(20)
	v_mfma_f32_16x16x32_bf16 v[8:11], v[136:139], v[128:131], v[8:11]
	v_mfma_f32_16x16x32_bf16 v[12:15], v[140:143], v[128:131], v[12:15]
	v_mfma_f32_16x16x32_bf16 v[0:3], v[136:139], v[132:135], v[0:3]
	v_mfma_f32_16x16x32_bf16 v[4:7], v[140:143], v[132:135], v[4:7]
	s_waitcnt vmcnt(16)
	v_mfma_f32_16x16x32_bf16 v[8:11], v[152:155], v[144:147], v[8:11]
	v_mfma_f32_16x16x32_bf16 v[12:15], v[156:159], v[144:147], v[12:15]
	v_mfma_f32_16x16x32_bf16 v[0:3], v[152:155], v[148:151], v[0:3]
	v_mfma_f32_16x16x32_bf16 v[4:7], v[156:159], v[148:151], v[4:7]
	global_load_dwordx4 v[128:131], v[160:161], off offset:1024
	global_load_dwordx4 v[132:135], v[162:163], off offset:1024
	global_load_dwordx4 v[136:139], v[164:165], off offset:1024
	global_load_dwordx4 v[140:143], v[166:167], off offset:1024
	global_load_dwordx4 v[144:147], v[160:161], off offset:1088
	global_load_dwordx4 v[148:151], v[162:163], off offset:1088
	global_load_dwordx4 v[152:155], v[164:165], off offset:1088
	global_load_dwordx4 v[156:159], v[166:167], off offset:1088
	s_waitcnt vmcnt(20)
	v_mfma_f32_16x16x32_bf16 v[8:11], v[72:75], v[64:67], v[8:11]
	v_mfma_f32_16x16x32_bf16 v[12:15], v[76:79], v[64:67], v[12:15]
	v_mfma_f32_16x16x32_bf16 v[0:3], v[72:75], v[68:71], v[0:3]
	v_mfma_f32_16x16x32_bf16 v[4:7], v[76:79], v[68:71], v[4:7]
	s_waitcnt vmcnt(16)
	v_mfma_f32_16x16x32_bf16 v[8:11], v[88:91], v[80:83], v[8:11]
	v_mfma_f32_16x16x32_bf16 v[12:15], v[92:95], v[80:83], v[12:15]
	v_mfma_f32_16x16x32_bf16 v[0:3], v[88:91], v[84:87], v[0:3]
	v_mfma_f32_16x16x32_bf16 v[4:7], v[92:95], v[84:87], v[4:7]
	global_load_dwordx4 v[64:67], v[160:161], off offset:1152
	global_load_dwordx4 v[68:71], v[162:163], off offset:1152
	global_load_dwordx4 v[72:75], v[164:165], off offset:1152
	global_load_dwordx4 v[76:79], v[166:167], off offset:1152
	global_load_dwordx4 v[80:83], v[160:161], off offset:1216
	global_load_dwordx4 v[84:87], v[162:163], off offset:1216
	global_load_dwordx4 v[88:91], v[164:165], off offset:1216
	global_load_dwordx4 v[92:95], v[166:167], off offset:1216
	s_waitcnt vmcnt(20)
	v_mfma_f32_16x16x32_bf16 v[8:11], v[104:107], v[96:99], v[8:11]
	v_mfma_f32_16x16x32_bf16 v[12:15], v[108:111], v[96:99], v[12:15]
	v_mfma_f32_16x16x32_bf16 v[0:3], v[104:107], v[100:103], v[0:3]
	v_mfma_f32_16x16x32_bf16 v[4:7], v[108:111], v[100:103], v[4:7]
	s_waitcnt vmcnt(16)
	v_mfma_f32_16x16x32_bf16 v[8:11], v[120:123], v[112:115], v[8:11]
	v_mfma_f32_16x16x32_bf16 v[12:15], v[124:127], v[112:115], v[12:15]
	v_mfma_f32_16x16x32_bf16 v[0:3], v[120:123], v[116:119], v[0:3]
	v_mfma_f32_16x16x32_bf16 v[4:7], v[124:127], v[116:119], v[4:7]
	global_load_dwordx4 v[96:99], v[160:161], off offset:1280
	global_load_dwordx4 v[100:103], v[162:163], off offset:1280
	global_load_dwordx4 v[104:107], v[164:165], off offset:1280
	global_load_dwordx4 v[108:111], v[166:167], off offset:1280
	global_load_dwordx4 v[112:115], v[160:161], off offset:1344
	global_load_dwordx4 v[116:119], v[162:163], off offset:1344
	global_load_dwordx4 v[120:123], v[164:165], off offset:1344
	global_load_dwordx4 v[124:127], v[166:167], off offset:1344
	s_waitcnt vmcnt(20)
	v_mfma_f32_16x16x32_bf16 v[8:11], v[136:139], v[128:131], v[8:11]
	v_mfma_f32_16x16x32_bf16 v[12:15], v[140:143], v[128:131], v[12:15]
	v_mfma_f32_16x16x32_bf16 v[0:3], v[136:139], v[132:135], v[0:3]
	v_mfma_f32_16x16x32_bf16 v[4:7], v[140:143], v[132:135], v[4:7]
	s_waitcnt vmcnt(16)
	v_mfma_f32_16x16x32_bf16 v[8:11], v[152:155], v[144:147], v[8:11]
	v_mfma_f32_16x16x32_bf16 v[12:15], v[156:159], v[144:147], v[12:15]
	v_mfma_f32_16x16x32_bf16 v[0:3], v[152:155], v[148:151], v[0:3]
	v_mfma_f32_16x16x32_bf16 v[4:7], v[156:159], v[148:151], v[4:7]
	global_load_dwordx4 v[128:131], v[160:161], off offset:1408
	global_load_dwordx4 v[132:135], v[162:163], off offset:1408
	global_load_dwordx4 v[136:139], v[164:165], off offset:1408
	global_load_dwordx4 v[140:143], v[166:167], off offset:1408
	global_load_dwordx4 v[144:147], v[160:161], off offset:1472
	global_load_dwordx4 v[148:151], v[162:163], off offset:1472
	global_load_dwordx4 v[152:155], v[164:165], off offset:1472
	global_load_dwordx4 v[156:159], v[166:167], off offset:1472
	s_waitcnt vmcnt(20)
	v_mfma_f32_16x16x32_bf16 v[8:11], v[72:75], v[64:67], v[8:11]
	v_mfma_f32_16x16x32_bf16 v[12:15], v[76:79], v[64:67], v[12:15]
	v_mfma_f32_16x16x32_bf16 v[0:3], v[72:75], v[68:71], v[0:3]
	v_mfma_f32_16x16x32_bf16 v[4:7], v[76:79], v[68:71], v[4:7]
	s_waitcnt vmcnt(16)
	v_mfma_f32_16x16x32_bf16 v[8:11], v[88:91], v[80:83], v[8:11]
	v_mfma_f32_16x16x32_bf16 v[12:15], v[92:95], v[80:83], v[12:15]
	v_mfma_f32_16x16x32_bf16 v[0:3], v[88:91], v[84:87], v[0:3]
	v_mfma_f32_16x16x32_bf16 v[4:7], v[92:95], v[84:87], v[4:7]
	global_load_dwordx4 v[64:67], v[160:161], off offset:1536
	global_load_dwordx4 v[68:71], v[162:163], off offset:1536
	global_load_dwordx4 v[72:75], v[164:165], off offset:1536
	global_load_dwordx4 v[76:79], v[166:167], off offset:1536
	global_load_dwordx4 v[80:83], v[160:161], off offset:1600
	global_load_dwordx4 v[84:87], v[162:163], off offset:1600
	global_load_dwordx4 v[88:91], v[164:165], off offset:1600
	global_load_dwordx4 v[92:95], v[166:167], off offset:1600
	s_waitcnt vmcnt(20)
	v_mfma_f32_16x16x32_bf16 v[8:11], v[104:107], v[96:99], v[8:11]
	v_mfma_f32_16x16x32_bf16 v[12:15], v[108:111], v[96:99], v[12:15]
	v_mfma_f32_16x16x32_bf16 v[0:3], v[104:107], v[100:103], v[0:3]
	v_mfma_f32_16x16x32_bf16 v[4:7], v[108:111], v[100:103], v[4:7]
	s_waitcnt vmcnt(16)
	v_mfma_f32_16x16x32_bf16 v[8:11], v[120:123], v[112:115], v[8:11]
	v_mfma_f32_16x16x32_bf16 v[12:15], v[124:127], v[112:115], v[12:15]
	v_mfma_f32_16x16x32_bf16 v[0:3], v[120:123], v[116:119], v[0:3]
	v_mfma_f32_16x16x32_bf16 v[4:7], v[124:127], v[116:119], v[4:7]
	global_load_dwordx4 v[96:99], v[160:161], off offset:1664
	global_load_dwordx4 v[100:103], v[162:163], off offset:1664
	global_load_dwordx4 v[104:107], v[164:165], off offset:1664
	global_load_dwordx4 v[108:111], v[166:167], off offset:1664
	global_load_dwordx4 v[112:115], v[160:161], off offset:1728
	global_load_dwordx4 v[116:119], v[162:163], off offset:1728
	global_load_dwordx4 v[120:123], v[164:165], off offset:1728
	global_load_dwordx4 v[124:127], v[166:167], off offset:1728
	s_waitcnt vmcnt(20)
	v_mfma_f32_16x16x32_bf16 v[8:11], v[136:139], v[128:131], v[8:11]
	v_mfma_f32_16x16x32_bf16 v[12:15], v[140:143], v[128:131], v[12:15]
	v_mfma_f32_16x16x32_bf16 v[0:3], v[136:139], v[132:135], v[0:3]
	v_mfma_f32_16x16x32_bf16 v[4:7], v[140:143], v[132:135], v[4:7]
	s_waitcnt vmcnt(16)
	v_mfma_f32_16x16x32_bf16 v[8:11], v[152:155], v[144:147], v[8:11]
	v_mfma_f32_16x16x32_bf16 v[12:15], v[156:159], v[144:147], v[12:15]
	v_mfma_f32_16x16x32_bf16 v[0:3], v[152:155], v[148:151], v[0:3]
	v_mfma_f32_16x16x32_bf16 v[4:7], v[156:159], v[148:151], v[4:7]
	global_load_dwordx4 v[128:131], v[160:161], off offset:1792
	global_load_dwordx4 v[132:135], v[162:163], off offset:1792
	global_load_dwordx4 v[136:139], v[164:165], off offset:1792
	global_load_dwordx4 v[140:143], v[166:167], off offset:1792
	global_load_dwordx4 v[144:147], v[160:161], off offset:1856
	global_load_dwordx4 v[148:151], v[162:163], off offset:1856
	global_load_dwordx4 v[152:155], v[164:165], off offset:1856
	global_load_dwordx4 v[156:159], v[166:167], off offset:1856
	s_waitcnt vmcnt(20)
	v_mfma_f32_16x16x32_bf16 v[8:11], v[72:75], v[64:67], v[8:11]
	v_mfma_f32_16x16x32_bf16 v[12:15], v[76:79], v[64:67], v[12:15]
	v_mfma_f32_16x16x32_bf16 v[0:3], v[72:75], v[68:71], v[0:3]
	v_mfma_f32_16x16x32_bf16 v[4:7], v[76:79], v[68:71], v[4:7]
	s_waitcnt vmcnt(16)
	v_mfma_f32_16x16x32_bf16 v[8:11], v[88:91], v[80:83], v[8:11]
	v_mfma_f32_16x16x32_bf16 v[12:15], v[92:95], v[80:83], v[12:15]
	v_mfma_f32_16x16x32_bf16 v[0:3], v[88:91], v[84:87], v[0:3]
	v_mfma_f32_16x16x32_bf16 v[4:7], v[92:95], v[84:87], v[4:7]
	global_load_dwordx4 v[64:67], v[160:161], off offset:1920
	global_load_dwordx4 v[68:71], v[162:163], off offset:1920
	global_load_dwordx4 v[72:75], v[164:165], off offset:1920
	global_load_dwordx4 v[76:79], v[166:167], off offset:1920
	global_load_dwordx4 v[80:83], v[160:161], off offset:1984
	global_load_dwordx4 v[84:87], v[162:163], off offset:1984
	global_load_dwordx4 v[88:91], v[164:165], off offset:1984
	global_load_dwordx4 v[92:95], v[166:167], off offset:1984
	s_waitcnt vmcnt(20)
	v_mfma_f32_16x16x32_bf16 v[8:11], v[104:107], v[96:99], v[8:11]
	v_mfma_f32_16x16x32_bf16 v[12:15], v[108:111], v[96:99], v[12:15]
	v_mfma_f32_16x16x32_bf16 v[0:3], v[104:107], v[100:103], v[0:3]
	v_mfma_f32_16x16x32_bf16 v[4:7], v[108:111], v[100:103], v[4:7]
	s_waitcnt vmcnt(16)
	v_mfma_f32_16x16x32_bf16 v[8:11], v[120:123], v[112:115], v[8:11]
	v_mfma_f32_16x16x32_bf16 v[12:15], v[124:127], v[112:115], v[12:15]
	v_mfma_f32_16x16x32_bf16 v[0:3], v[120:123], v[116:119], v[0:3]
	v_mfma_f32_16x16x32_bf16 v[4:7], v[124:127], v[116:119], v[4:7]
	s_waitcnt vmcnt(12)
	v_mfma_f32_16x16x32_bf16 v[8:11], v[136:139], v[128:131], v[8:11]
	v_mfma_f32_16x16x32_bf16 v[12:15], v[140:143], v[128:131], v[12:15]
	v_mfma_f32_16x16x32_bf16 v[0:3], v[136:139], v[132:135], v[0:3]
	v_mfma_f32_16x16x32_bf16 v[4:7], v[140:143], v[132:135], v[4:7]
	s_waitcnt vmcnt(8)
	v_mfma_f32_16x16x32_bf16 v[8:11], v[152:155], v[144:147], v[8:11]
	v_mfma_f32_16x16x32_bf16 v[12:15], v[156:159], v[144:147], v[12:15]
	v_mfma_f32_16x16x32_bf16 v[0:3], v[152:155], v[148:151], v[0:3]
	v_mfma_f32_16x16x32_bf16 v[4:7], v[156:159], v[148:151], v[4:7]
	s_waitcnt vmcnt(4)
	v_mfma_f32_16x16x32_bf16 v[8:11], v[72:75], v[64:67], v[8:11]
	v_mfma_f32_16x16x32_bf16 v[12:15], v[76:79], v[64:67], v[12:15]
	v_mfma_f32_16x16x32_bf16 v[0:3], v[72:75], v[68:71], v[0:3]
	v_mfma_f32_16x16x32_bf16 v[4:7], v[76:79], v[68:71], v[4:7]
	s_waitcnt vmcnt(0)
	v_mfma_f32_16x16x32_bf16 v[8:11], v[88:91], v[80:83], v[8:11]
	v_mfma_f32_16x16x32_bf16 v[12:15], v[92:95], v[80:83], v[12:15]
	v_mfma_f32_16x16x32_bf16 v[0:3], v[88:91], v[84:87], v[0:3]
	v_mfma_f32_16x16x32_bf16 v[4:7], v[92:95], v[84:87], v[4:7]
	s_movk_i32 s4, 0x800
	s_mov_b32 s5, 0
	v_or_b32_e32 v16, v22, v20
	v_add_u32_e32 v16, v16, v21
	v_ashrrev_i32_e32 v17, 31, v16
	s_waitcnt lgkmcnt(0)
	v_lshl_add_u64 v[18:19], v[16:17], 2, s[24:25]
	global_load_dword v17, v[18:19], off
	v_and_b32_e32 v28, 3, v23
	v_lshlrev_b32_e32 v27, 2, v28
	v_lshlrev_b32_e32 v168, 3, v28
	s_waitcnt vmcnt(0)
	v_cvt_f32_i32_e32 v29, v17
	v_cvt_f32_ubyte0_e32 v17, v27
	v_mul_f32_e32 v18, 0xbf549a78, v17
	v_cmp_gt_f32_e32 vcc, s86, v18
	s_nop 1
	v_cndmask_b32_e32 v18, 0, v180, vcc
	v_fmac_f32_e32 v18, 0xbf549a78, v17
	v_exp_f32_e32 v17, v18
	v_cndmask_b32_e32 v18, 0, v179, vcc
	v_ldexp_f32 v17, v17, v18
	v_mul_f32_e32 v18, v17, v29
	v_mul_f32_e32 v19, 0.15915494, v18
	v_rndne_f32_e32 v19, v19
	v_fma_f32 v19, v18, 0.15915494, -v19
	v_fmac_f32_e32 v19, 0x31dc9c88, v18
	v_or_b32_e32 v18, 1, v27
	v_cvt_f32_ubyte0_e32 v18, v18
	v_sin_f32_e32 v20, v19
	v_cos_f32_e32 v24, v19
	v_mul_f32_e32 v19, 0xbf549a78, v18
	v_cmp_gt_f32_e32 vcc, s86, v19
	s_nop 1
	v_cndmask_b32_e32 v19, 0, v180, vcc
	v_fmac_f32_e32 v19, 0xbf549a78, v18
	v_exp_f32_e32 v18, v19
	v_cndmask_b32_e32 v19, 0, v179, vcc
	v_ldexp_f32 v22, v18, v19
	v_mul_f32_e32 v18, v22, v29
	v_mul_f32_e32 v19, 0.15915494, v18
	v_rndne_f32_e32 v19, v19
	v_fma_f32 v19, v18, 0.15915494, -v19
	v_fmac_f32_e32 v19, 0x31dc9c88, v18
	v_sin_f32_e32 v21, v19
	v_cos_f32_e32 v25, v19
	v_pk_mul_f32 v[18:19], v[12:13], v[20:21]
	v_pk_mul_f32 v[12:13], v[12:13], v[24:25]
	v_pk_fma_f32 v[18:19], v[8:9], v[24:25], v[18:19] neg_lo:[0,0,1] neg_hi:[0,0,1]
	v_pk_fma_f32 v[12:13], v[8:9], v[20:21], v[12:13]
	v_or_b32_e32 v8, 2, v27
	v_cvt_f32_ubyte0_e32 v8, v8
	v_mul_f32_e32 v9, 0xbf549a78, v8
	v_cmp_gt_f32_e32 vcc, s86, v9
	v_cvt_pk_bf16_f32 v12, v12, v13
	v_cvt_pk_bf16_f32 v18, v18, v19
	v_cndmask_b32_e32 v9, 0, v180, vcc
	v_fmac_f32_e32 v9, 0xbf549a78, v8
	v_exp_f32_e32 v8, v9
	v_cndmask_b32_e32 v9, 0, v179, vcc
	v_ldexp_f32 v23, v8, v9
	v_mul_f32_e32 v8, v23, v29
	v_mul_f32_e32 v9, 0.15915494, v8
	v_rndne_f32_e32 v9, v9
	v_fma_f32 v9, v8, 0.15915494, -v9
	v_fmac_f32_e32 v9, 0x31dc9c88, v8
	v_sin_f32_e32 v8, v9
	v_cos_f32_e32 v26, v9
	v_or_b32_e32 v9, 3, v27
	v_cvt_f32_ubyte0_e32 v9, v9
	v_mul_f32_e32 v20, 0xbf549a78, v9
	v_cmp_gt_f32_e32 vcc, s86, v20
	s_nop 1
	v_cndmask_b32_e32 v20, 0, v180, vcc
	v_fmac_f32_e32 v20, 0xbf549a78, v9
	v_exp_f32_e32 v9, v20
	v_cndmask_b32_e32 v20, 0, v179, vcc
	v_ldexp_f32 v24, v9, v20
	v_mul_f32_e32 v9, v24, v29
	v_mul_f32_e32 v20, 0.15915494, v9
	v_rndne_f32_e32 v20, v20
	v_fma_f32 v20, v9, 0.15915494, -v20
	v_fmac_f32_e32 v20, 0x31dc9c88, v9
	v_sin_f32_e32 v9, v20
	v_cos_f32_e32 v27, v20
	v_pk_mul_f32 v[20:21], v[14:15], v[8:9]
	v_pk_mul_f32 v[14:15], v[14:15], v[26:27]
	v_pk_fma_f32 v[20:21], v[10:11], v[26:27], v[20:21] neg_lo:[0,0,1] neg_hi:[0,0,1]
	v_pk_fma_f32 v[10:11], v[10:11], v[8:9], v[14:15]
	v_mov_b64_e32 v[8:9], s[62:63]
	v_mad_i64_i32 v[14:15], s[4:5], v16, s59, v[8:9]
	v_lshl_add_u64 v[14:15], v[14:15], 0, v[168:169]
	s_mov_b32 s4, 0x38e2000
	v_lshl_add_u64 v[26:27], v[14:15], 0, s[94:95]
	v_add_co_u32_e32 v14, vcc, s4, v14
	v_cvt_pk_bf16_f32 v13, v10, v11
	v_or_b32_e32 v10, 16, v16
	v_cvt_pk_bf16_f32 v19, v20, v21
	v_addc_co_u32_e32 v15, vcc, 0, v15, vcc
	v_ashrrev_i32_e32 v11, 31, v10
	global_store_dwordx2 v[14:15], v[18:19], off offset:2048
	global_store_dwordx2 v[26:27], v[12:13], off offset:32
	v_lshl_add_u64 v[12:13], v[10:11], 2, s[24:25]
	global_load_dword v11, v[12:13], off
	s_waitcnt vmcnt(0)
	v_cvt_f32_i32_e32 v11, v11
	v_mul_f32_e32 v12, v17, v11
	v_mul_f32_e32 v13, 0.15915494, v12
	v_rndne_f32_e32 v13, v13
	v_fma_f32 v13, v12, 0.15915494, -v13
	v_fmac_f32_e32 v13, 0x31dc9c88, v12
	v_sin_f32_e32 v12, v13
	v_cos_f32_e32 v14, v13
	v_mul_f32_e32 v13, v22, v11
	v_mul_f32_e32 v15, 0.15915494, v13
	v_rndne_f32_e32 v15, v15
	v_fma_f32 v15, v13, 0.15915494, -v15
	v_fmac_f32_e32 v15, 0x31dc9c88, v13
	v_sin_f32_e32 v13, v15
	v_cos_f32_e32 v15, v15
	v_pk_mul_f32 v[16:17], v[4:5], v[12:13]
	v_pk_mul_f32 v[4:5], v[4:5], v[14:15]
	v_pk_fma_f32 v[16:17], v[0:1], v[14:15], v[16:17] neg_lo:[0,0,1] neg_hi:[0,0,1]
	v_pk_fma_f32 v[0:1], v[0:1], v[12:13], v[4:5]
	v_mul_f32_e32 v4, v23, v11
	v_mul_f32_e32 v5, 0.15915494, v4
	v_rndne_f32_e32 v5, v5
	v_fma_f32 v5, v4, 0.15915494, -v5
	v_fmac_f32_e32 v5, 0x31dc9c88, v4
	v_sin_f32_e32 v4, v5
	v_cos_f32_e32 v12, v5
	v_mul_f32_e32 v5, v24, v11
	v_mul_f32_e32 v11, 0.15915494, v5
	v_rndne_f32_e32 v11, v11
	v_fma_f32 v11, v5, 0.15915494, -v11
	v_fmac_f32_e32 v11, 0x31dc9c88, v5
	v_sin_f32_e32 v5, v11
	v_cos_f32_e32 v13, v11
	v_cvt_pk_bf16_f32 v0, v0, v1
	v_pk_mul_f32 v[14:15], v[6:7], v[4:5]
	v_pk_mul_f32 v[6:7], v[6:7], v[12:13]
	v_pk_fma_f32 v[14:15], v[2:3], v[12:13], v[14:15] neg_lo:[0,0,1] neg_hi:[0,0,1]
	v_pk_fma_f32 v[2:3], v[2:3], v[4:5], v[6:7]
	v_mad_i64_i32 v[4:5], s[4:5], v10, s59, v[8:9]
	v_lshl_add_u64 v[4:5], v[4:5], 0, v[168:169]
	v_lshl_add_u64 v[6:7], v[4:5], 0, s[94:95]
	v_add_co_u32_e32 v4, vcc, 0x38e2000, v4
	v_cvt_pk_bf16_f32 v8, v16, v17
	v_cvt_pk_bf16_f32 v9, v14, v15
	v_addc_co_u32_e32 v5, vcc, 0, v5, vcc
	v_cvt_pk_bf16_f32 v1, v2, v3
	global_store_dwordx2 v[4:5], v[8:9], off offset:2048
	global_store_dwordx2 v[6:7], v[0:1], off offset:32
